# res_fixup: warm-up prefetch of all partial-slab and X lines of an item right after its first load
# speedup vs baseline: 1.0370x; 1.0043x over previous
; template <class FrameT>
; __device__ __forceinline__ void res_fixup(FrameT& F, const EpiRes& E, const pg8::DpSplit& S) {
;     ...
;     for (int item = blockIdx.x; item < nleft * 8; item += F.G) {
;         const int j = item >> 3, ai = (item >> 2) & 1, m = item & 3;
;         pg8::Unit u; S.unit_of(S.G + j, u);
;         const int r = u.pm * 256 + wr * 64 + fr + ai * 128 + m * 16, col0 = u.pn * 256 + wc * 32 + 8 * fq;
;         float q = 0.f;
; #pragma unroll
;         for (int bj = 0; bj < 2; ++bj) {
;             f32x4 a0 = {0.f, 0.f, 0.f, 0.f}, a1 = {0.f, 0.f, 0.f, 0.f};
; #pragma unroll
;             for (int p = 0; p < 4; ++p) {
;                 const float* sp = S.slab + (size_t)(4 * j + p) * 65536 + (size_t)(((ai * 2 + bj) * 4 + m) * 2048) + tid * 4;
;                 const u32x4 w = __builtin_nontemporal_load((const u32x4*)sp);
;                 a0 += (f32x4){__uint_as_float(w.x << 16), __uint_as_float(w.x & 0xffff0000u), __uint_as_float(w.y << 16), __uint_as_float(w.y & 0xffff0000u)};
;                 a1 += (f32x4){__uint_as_float(w.z << 16), __uint_as_float(w.z & 0xffff0000u), __uint_as_float(w.w << 16), __uint_as_float(w.w & 0xffff0000u)};
;             }
;             float* xp = E.X + (size_t)r * D + col0 + bj * 128;
;             f32x4 v0 = *(f32x4*)xp, v1 = *(f32x4*)(xp + 4);
.LBB0_506:
	s_add_i32 s2, s9, s2
	s_ashr_i32 s3, s2, 31
	s_lshr_b32 s3, s3, 27
	s_add_i32 s3, s2, s3
	s_ashr_i32 s9, s3, 5
	s_lshl_b32 s9, s9, 3
	s_sub_i32 s20, 0x45, s9
	s_min_i32 s20, s20, 8
	s_abs_i32 s22, s20
	v_cvt_f32_u32_e32 v0, s22
	s_sub_i32 s23, 0, s22
	s_andn2_b32 s3, s3, 31
	s_sub_i32 s2, s2, s3
	v_rcp_iflag_f32_e32 v0, v0
	s_abs_i32 s21, s2
	s_xor_b32 s3, s2, s20
	s_bfe_u32 s18, s17, 0x10002
	v_mul_f32_e32 v0, 0x4f7ffffe, v0
	v_cvt_u32_f32_e32 v0, v0
	s_and_b32 s19, s17, 3
	s_ashr_i32 s3, s3, 31
	v_mov_b32_e32 v175, v174
	v_readfirstlane_b32 s24, v0
	s_mul_i32 s23, s23, s24
	s_mul_hi_u32 s23, s24, s23
	s_add_i32 s24, s24, s23
	s_mul_hi_u32 s23, s21, s24
	s_mul_i32 s24, s23, s22
	s_sub_i32 s21, s21, s24
	s_add_i32 s24, s23, 1
	s_sub_i32 s25, s21, s22
	s_cmp_ge_u32 s21, s22
	s_cselect_b32 s23, s24, s23
	s_cselect_b32 s21, s25, s21
	s_add_i32 s24, s23, 1
	s_cmp_ge_u32 s21, s22
	s_cselect_b32 s21, s24, s23
	s_xor_b32 s21, s21, s3
	s_sub_i32 s3, s21, s3
	s_mul_i32 s20, s3, s20
	s_sub_i32 s2, s2, s20
	s_add_i32 s9, s9, s2
	s_lshl_b32 s2, s9, 8
	s_lshl_b32 s9, s18, 7
	s_lshl_b32 s20, s8, 2
	v_lshl_or_b32 v0, s19, 4, v22
	s_or_b32 s2, s2, s9
	s_ashr_i32 s21, s20, 31
	s_lshl_b32 s8, s19, 13
	s_lshl_b32 s9, s18, 16
	v_add_u32_e32 v8, s2, v0
	v_lshl_or_b32 v2, s3, 8, v23
	s_lshl_b64 s[2:3], s[20:21], 18
	s_or_b32 s8, s9, s8
	s_add_u32 s8, s72, s8
	s_addc_u32 s9, s73, 0
	s_waitcnt lgkmcnt(0)
	v_lshl_add_u64 v[0:1], v[4:5], 2, s[8:9]
	v_lshl_add_u64 v[10:11], v[0:1], 0, s[2:3]
	global_load_dwordx4 v[10:13], v[10:11], off nt
	s_or_b32 s8, s20, 1
	s_ashr_i32 s9, s8, 31
	s_lshl_b64 s[8:9], s[8:9], 18
	s_or_b32 s18, s20, 2
	s_ashr_i32 s19, s18, 31
	s_lshl_b64 s[18:19], s[18:19], 18
	s_or_b32 s20, s20, 3
	s_ashr_i32 s21, s20, 31
	s_lshl_b64 s[20:21], s[20:21], 18
	v_ashrrev_i32_e32 v9, 31, v8
	v_ashrrev_i32_e32 v3, 31, v2
	s_mov_b64 s[22:23], 0x8000
	v_lshl_add_u64 v[32:33], v[0:1], 0, s[8:9]
	global_load_dwordx4 v[36:39], v[32:33], off
	v_lshl_add_u64 v[34:35], v[32:33], 0, s[22:23]
	global_load_dwordx4 v[36:39], v[34:35], off
	v_lshl_add_u64 v[32:33], v[0:1], 0, s[18:19]
	global_load_dwordx4 v[36:39], v[32:33], off
	v_lshl_add_u64 v[34:35], v[32:33], 0, s[22:23]
	global_load_dwordx4 v[36:39], v[34:35], off
	v_lshl_add_u64 v[32:33], v[0:1], 0, s[20:21]
	global_load_dwordx4 v[36:39], v[32:33], off
	v_lshl_add_u64 v[34:35], v[32:33], 0, s[22:23]
	global_load_dwordx4 v[36:39], v[34:35], off
	v_lshl_add_u64 v[32:33], v[0:1], 0, s[2:3]
	v_lshl_add_u64 v[34:35], v[32:33], 0, s[22:23]
	global_load_dwordx4 v[36:39], v[34:35], off
	v_lshlrev_b64 v[32:33], 12, v[8:9]
	v_lshl_add_u64 v[32:33], s[10:11], 0, v[32:33]
	v_lshl_add_u64 v[32:33], v[2:3], 2, v[32:33]
	global_load_dwordx4 v[36:39], v[32:33], off
	global_load_dwordx4 v[36:39], v[32:33], off offset:512
	s_waitcnt vmcnt(0)
	v_lshlrev_b32_e32 v14, 16, v10
	v_and_b32_e32 v15, 0xffff0000, v10
	v_lshlrev_b32_e32 v10, 16, v11
	v_and_b32_e32 v11, 0xffff0000, v11
	v_pk_add_f32 v[16:17], v[10:11], 0 op_sel_hi:[1,0]
	v_lshlrev_b32_e32 v10, 16, v12
	v_and_b32_e32 v11, 0xffff0000, v12
	v_lshlrev_b32_e32 v12, 16, v13
	v_and_b32_e32 v13, 0xffff0000, v13
	v_pk_add_f32 v[20:21], v[10:11], 0 op_sel_hi:[1,0]
	v_lshl_add_u64 v[10:11], v[0:1], 0, s[8:9]
	v_pk_add_f32 v[18:19], v[12:13], 0 op_sel_hi:[1,0]
	global_load_dwordx4 v[10:13], v[10:11], off nt
	v_pk_add_f32 v[14:15], v[14:15], 0 op_sel_hi:[1,0]
	s_waitcnt vmcnt(0)
	v_lshlrev_b32_e32 v24, 16, v10
	v_and_b32_e32 v25, 0xffff0000, v10
	v_lshlrev_b32_e32 v10, 16, v11
	v_and_b32_e32 v11, 0xffff0000, v11
	v_pk_add_f32 v[16:17], v[16:17], v[10:11]
	v_lshlrev_b32_e32 v10, 16, v12
	v_and_b32_e32 v11, 0xffff0000, v12
	v_lshlrev_b32_e32 v12, 16, v13
	v_and_b32_e32 v13, 0xffff0000, v13
	v_pk_add_f32 v[20:21], v[20:21], v[10:11]
	v_lshl_add_u64 v[10:11], v[0:1], 0, s[18:19]
	v_pk_add_f32 v[18:19], v[18:19], v[12:13]
	global_load_dwordx4 v[10:13], v[10:11], off nt
	v_pk_add_f32 v[14:15], v[14:15], v[24:25]
	s_waitcnt vmcnt(0)
	v_lshlrev_b32_e32 v24, 16, v10
	v_and_b32_e32 v25, 0xffff0000, v10
	v_pk_add_f32 v[24:25], v[14:15], v[24:25]
	v_lshlrev_b32_e32 v14, 16, v12
	v_and_b32_e32 v15, 0xffff0000, v12
	v_lshlrev_b32_e32 v12, 16, v13
	v_and_b32_e32 v13, 0xffff0000, v13
	v_lshlrev_b32_e32 v10, 16, v11
	v_and_b32_e32 v11, 0xffff0000, v11
	v_pk_add_f32 v[18:19], v[18:19], v[12:13]
	v_lshl_add_u64 v[12:13], v[0:1], 0, s[20:21]
	v_pk_add_f32 v[10:11], v[16:17], v[10:11]
	v_pk_add_f32 v[20:21], v[20:21], v[14:15]
	global_load_dwordx4 v[14:17], v[12:13], off nt
	s_waitcnt vmcnt(0)
	v_lshlrev_b32_e32 v12, 16, v14
	v_and_b32_e32 v13, 0xffff0000, v14
	v_lshlrev_b32_e32 v14, 16, v15
	v_and_b32_e32 v15, 0xffff0000, v15
	v_pk_add_f32 v[14:15], v[10:11], v[14:15]
	v_lshlrev_b32_e32 v10, 16, v16
	v_and_b32_e32 v11, 0xffff0000, v16
	v_pk_add_f32 v[12:13], v[24:25], v[12:13]
	v_lshlrev_b32_e32 v24, 16, v17
	v_and_b32_e32 v25, 0xffff0000, v17
	v_pk_add_f32 v[16:17], v[20:21], v[10:11]
	v_lshlrev_b64 v[10:11], 12, v[8:9]
	v_lshl_add_u64 v[10:11], s[10:11], 0, v[10:11]
	v_lshl_add_u64 v[10:11], v[2:3], 2, v[10:11]
	v_pk_add_f32 v[18:19], v[18:19], v[24:25]
	global_load_dwordx4 v[24:27], v[10:11], off offset:16
	global_load_dwordx4 v[28:31], v[10:11], off
	s_waitcnt vmcnt(1)
; __device__ __forceinline__ unsigned pk2(float lo, float hi) { unsigned r; asm("v_cvt_pk_bf16_f32 %0, %1, %2" : "=v"(r) : "v"(lo), "v"(hi)); return r; }
; template <class FrameT>
; __device__ __forceinline__ void res_fixup(FrameT& F, const EpiRes& E, const pg8::DpSplit& S) {
;     ...
; #pragma unroll
;         for (int bj = 0; bj < 2; ++bj) {
;             f32x4 a0 = {0.f, 0.f, 0.f, 0.f}, a1 = {0.f, 0.f, 0.f, 0.f};
; #pragma unroll
;             for (int p = 0; p < 4; ++p) {
;                 const float* sp = S.slab + (size_t)(4 * j + p) * 65536 + (size_t)(((ai * 2 + bj) * 4 + m) * 2048) + tid * 4;
;                 const u32x4 w = __builtin_nontemporal_load((const u32x4*)sp);
;                 a0 += (f32x4){__uint_as_float(w.x << 16), __uint_as_float(w.x & 0xffff0000u), __uint_as_float(w.y << 16), __uint_as_float(w.y & 0xffff0000u)};
;                 a1 += (f32x4){__uint_as_float(w.z << 16), __uint_as_float(w.z & 0xffff0000u), __uint_as_float(w.w << 16), __uint_as_float(w.w & 0xffff0000u)};
;             }
;             float* xp = E.X + (size_t)r * D + col0 + bj * 128;
;             f32x4 v0 = *(f32x4*)xp, v1 = *(f32x4*)(xp + 4);
;             v0 = v0 + a0 * E.scale; v1 = v1 + a1 * E.scale;
;             *(f32x4*)xp = v0; *(f32x4*)(xp + 4) = v1;
;             u32x4 w; w.x = pk2(v0[0], v0[1]); w.y = pk2(v0[2], v0[3]); w.z = pk2(v1[0], v1[1]); w.w = pk2(v1[2], v1[3]);
;             *(u32x4*)(E.XB + (size_t)r * D + col0 + bj * 128) = w;
;             q += (v0[0] * v0[0] + v0[1] * v0[1]) + (v0[2] * v0[2] + v0[3] * v0[3]) + (v1[0] * v1[0] + v1[1] * v1[1]) + (v1[2] * v1[2] + v1[3] * v1[3]);
;         }
;         q += __shfl_xor(q, 16); q += __shfl_xor(q, 32);
;         if (fq == 0) atomicAdd(E.ssn + r, q);
	v_pk_fma_f32 v[16:17], v[6:7], v[16:17], v[24:25]
	s_waitcnt vmcnt(0)
	v_pk_fma_f32 v[28:29], v[6:7], v[12:13], v[28:29]
	v_lshlrev_b64 v[12:13], 11, v[8:9]
	v_pk_fma_f32 v[30:31], v[174:175], v[14:15], v[30:31]
	v_lshl_add_u64 v[12:13], s[12:13], 0, v[12:13]
	v_lshl_add_u64 v[12:13], v[2:3], 1, v[12:13]
	v_mul_f32_e32 v2, v29, v29
	v_mul_f32_e32 v3, v31, v31
	v_fmac_f32_e32 v2, v28, v28
	v_fmac_f32_e32 v3, v30, v30
	v_add_f32_e32 v2, v2, v3
	v_mul_f32_e32 v3, v17, v17
	v_pk_fma_f32 v[18:19], v[174:175], v[18:19], v[26:27]
	v_fmac_f32_e32 v3, v16, v16
	v_add_f32_e32 v2, v3, v2
	v_mul_f32_e32 v3, v19, v19
	v_lshl_add_u64 v[14:15], v[0:1], 0, s[22:23]
	global_store_dwordx4 v[10:11], v[28:31], off
	global_store_dwordx4 v[10:11], v[16:19], off offset:16
	v_cvt_pk_bf16_f32 v24, v28, v29
	v_cvt_pk_bf16_f32 v25, v30, v31
	v_cvt_pk_bf16_f32 v26, v16, v17
	v_cvt_pk_bf16_f32 v27, v18, v19
	global_store_dwordx4 v[12:13], v[24:27], off
	v_fmac_f32_e32 v3, v18, v18
	v_lshl_add_u64 v[0:1], v[14:15], 0, s[2:3]
	v_add_f32_e32 v24, v3, v2
	global_load_dwordx4 v[0:3], v[0:1], off nt
	s_waitcnt vmcnt(0)
	v_lshlrev_b32_e32 v16, 16, v0
	v_and_b32_e32 v17, 0xffff0000, v0
	v_lshlrev_b32_e32 v0, 16, v1
	v_and_b32_e32 v1, 0xffff0000, v1
	v_pk_add_f32 v[18:19], v[0:1], 0 op_sel_hi:[1,0]
	v_lshlrev_b32_e32 v0, 16, v2
	v_and_b32_e32 v1, 0xffff0000, v2
	v_lshlrev_b32_e32 v2, 16, v3
	v_and_b32_e32 v3, 0xffff0000, v3
	v_pk_add_f32 v[26:27], v[0:1], 0 op_sel_hi:[1,0]
	v_lshl_add_u64 v[0:1], v[14:15], 0, s[8:9]
	v_pk_add_f32 v[20:21], v[2:3], 0 op_sel_hi:[1,0]
	global_load_dwordx4 v[0:3], v[0:1], off nt
	v_pk_add_f32 v[16:17], v[16:17], 0 op_sel_hi:[1,0]
	s_waitcnt vmcnt(0)
	v_lshlrev_b32_e32 v28, 16, v0
	v_and_b32_e32 v29, 0xffff0000, v0
	v_lshlrev_b32_e32 v0, 16, v1
	v_and_b32_e32 v1, 0xffff0000, v1
	v_pk_add_f32 v[18:19], v[18:19], v[0:1]
	v_lshlrev_b32_e32 v0, 16, v2
	v_and_b32_e32 v1, 0xffff0000, v2
	v_lshlrev_b32_e32 v2, 16, v3
	v_and_b32_e32 v3, 0xffff0000, v3
	v_pk_add_f32 v[26:27], v[26:27], v[0:1]
	v_lshl_add_u64 v[0:1], v[14:15], 0, s[18:19]
	v_pk_add_f32 v[20:21], v[20:21], v[2:3]
	global_load_dwordx4 v[0:3], v[0:1], off nt
	v_pk_add_f32 v[16:17], v[16:17], v[28:29]
	s_waitcnt vmcnt(0)
	v_lshlrev_b32_e32 v28, 16, v0
	v_and_b32_e32 v29, 0xffff0000, v0
	v_lshlrev_b32_e32 v0, 16, v1
	v_and_b32_e32 v1, 0xffff0000, v1
	v_pk_add_f32 v[18:19], v[18:19], v[0:1]
	v_lshlrev_b32_e32 v0, 16, v2
	v_and_b32_e32 v1, 0xffff0000, v2
	v_lshlrev_b32_e32 v2, 16, v3
	v_and_b32_e32 v3, 0xffff0000, v3
	v_pk_add_f32 v[26:27], v[26:27], v[0:1]
	v_lshl_add_u64 v[0:1], v[14:15], 0, s[20:21]
	v_pk_add_f32 v[20:21], v[20:21], v[2:3]
	global_load_dwordx4 v[0:3], v[0:1], off nt
	v_pk_add_f32 v[16:17], v[16:17], v[28:29]
	s_waitcnt vmcnt(0)
	v_lshlrev_b32_e32 v14, 16, v0
	v_and_b32_e32 v15, 0xffff0000, v0
	v_lshlrev_b32_e32 v0, 16, v1
	v_and_b32_e32 v1, 0xffff0000, v1
	v_pk_add_f32 v[14:15], v[16:17], v[14:15]
	v_pk_add_f32 v[16:17], v[18:19], v[0:1]
	v_lshlrev_b32_e32 v0, 16, v2
	v_and_b32_e32 v1, 0xffff0000, v2
	v_lshlrev_b32_e32 v2, 16, v3
	v_and_b32_e32 v3, 0xffff0000, v3
	v_pk_add_f32 v[18:19], v[26:27], v[0:1]
	v_pk_add_f32 v[20:21], v[20:21], v[2:3]
	global_load_dwordx4 v[0:3], v[10:11], off offset:528
	global_load_dwordx4 v[26:29], v[10:11], off offset:512
	s_waitcnt vmcnt(1)
	v_pk_fma_f32 v[2:3], v[174:175], v[20:21], v[2:3]
	s_waitcnt vmcnt(0)
	v_pk_fma_f32 v[16:17], v[174:175], v[16:17], v[28:29]
	v_pk_fma_f32 v[14:15], v[6:7], v[14:15], v[26:27]
	v_pk_fma_f32 v[0:1], v[6:7], v[18:19], v[0:1]
	global_store_dwordx4 v[10:11], v[14:17], off offset:512
	global_store_dwordx4 v[10:11], v[0:3], off offset:528
	v_mul_f32_e32 v10, v15, v15
	v_mul_f32_e32 v11, v17, v17
	v_cvt_pk_bf16_f32 v20, v0, v1
	v_fmac_f32_e32 v10, v14, v14
	v_fmac_f32_e32 v11, v16, v16
	v_mul_f32_e32 v1, v1, v1
	v_add_f32_e32 v10, v10, v11
	v_fmac_f32_e32 v1, v0, v0
	v_add_f32_e32 v0, v1, v10
	v_mul_f32_e32 v1, v3, v3
	v_fmac_f32_e32 v1, v2, v2
	v_cvt_pk_bf16_f32 v21, v2, v3
	v_add_f32_e32 v0, v1, v0
	v_xor_b32_e32 v1, 16, v196
	v_add_u32_e32 v2, 64, v197
	v_cmp_lt_i32_e32 vcc, v1, v2
	v_add_f32_e32 v0, v24, v0
	v_cvt_pk_bf16_f32 v18, v14, v15
	v_cvt_pk_bf16_f32 v19, v16, v17
	global_store_dwordx4 v[12:13], v[18:21], off offset:256
	v_cndmask_b32_e32 v1, v196, v1, vcc
	v_lshlrev_b32_e32 v1, 2, v1
	ds_bpermute_b32 v1, v1, v0
	s_waitcnt lgkmcnt(0)
	v_add_f32_e32 v0, v0, v1
	v_xor_b32_e32 v1, 32, v196
	v_cmp_lt_i32_e32 vcc, v1, v2
	s_nop 1
	v_cndmask_b32_e32 v1, v196, v1, vcc
	v_lshlrev_b32_e32 v1, 2, v1
	ds_bpermute_b32 v1, v1, v0
	s_and_saveexec_b64 s[2:3], s[6:7]
	s_cbranch_execz .LBB0_501
	v_lshl_add_u64 v[2:3], v[8:9], 2, s[14:15]
	s_waitcnt lgkmcnt(0)
	v_add_f32_e32 v0, v0, v1
	global_atomic_add_f32 v[2:3], v0, off
	s_branch .LBB0_501
